# strategy 7 instruction selection in diff-attention softmax: scalar v_fma pairs instead of v_pk_fma behind QK MFMAs; xor-32 row-max exchange via v_permlane32_swap instead of ds_bpermute; on top of stac
# speedup vs baseline: 1.0102x; 1.0005x over previous
; #define LAS __attribute__((address_space(3)))
; #define MFMA32(a, b, c) __builtin_amdgcn_mfma_f32_32x32x16_bf16((a), (b), (c), 0, 0, 0)
; template <bool SB>
; __device__ __forceinline__ void attn_unit(LAS unsigned char* lds, const bf16_t* qkv, bf16_t* merged, int b, int gi, int qb,
;                                           const float* gnorm, float lam, float outscale, const float* rel_bias) {
;     ...
;             const int s0 = 64 * kt + 32 * kb;
;             const bool skip = SB ? (s0 >= q0 + 31 || wdone) : (s0 > q0 + 31);
;             if (!skip) {
;                 f32x16 sacc;
; #pragma unroll
;                 for (int i = 0; i < 16; ++i) sacc[i] = 0.f;
; #pragma unroll
;                 for (int s = 0; s < 8; ++s) { const bf16x8 kf = *(LAS const bf16x8*)(stage + ((kbase ^ (unsigned)(s << 5)) + kb * 16384)); sacc = MFMA32(kf, qf[s], sacc); }
;     ...
;                     float tv[16];
;                     constexpr float C = QK_SCALE * LOG2E;
;                     if (s0 + 31 + 128 <= q0) { const float cb = tab[128];
; #pragma unroll
;                         for (int i = 0; i < 16; ++i) tv[i] = sacc[i] * C + cb;
.LBB0_153:
	s_add_i32 s81, s81, 0
	s_add_i32 s4, s78, 0xffffff61
	s_cmp_gt_u32 s4, s52
	v_add_u32_e32 v226, s81, v204
	v_add_u32_e32 v225, s81, v205
	v_add_u32_e32 v224, s81, v206
	v_add_u32_e32 v223, s81, v207
	v_add_u32_e32 v222, s81, v208
	v_add_u32_e32 v221, s81, v209
	v_add_u32_e32 v220, s81, v210
	v_add_u32_e32 v219, s81, v211
	s_cbranch_scc1 .LBB0_193
	ds_read_b128 v[2:5], v226 offset:16384
	ds_read_b128 v[6:9], v225 offset:16384
	s_cmp_le_u32 s78, s77
	s_mov_b64 s[4:5], -1
	s_waitcnt lgkmcnt(1)
	v_mfma_f32_32x32x16_bf16 v[144:159], v[2:5], v[184:187], 0
	s_waitcnt lgkmcnt(0)
	v_mfma_f32_32x32x16_bf16 v[144:159], v[6:9], v[160:163], v[144:159]
	ds_read_b128 v[2:5], v224 offset:16384
	ds_read_b128 v[6:9], v223 offset:16384
	s_waitcnt lgkmcnt(1)
	v_mfma_f32_32x32x16_bf16 v[144:159], v[2:5], v[164:167], v[144:159]
	s_waitcnt lgkmcnt(0)
	v_mfma_f32_32x32x16_bf16 v[144:159], v[6:9], v[168:171], v[144:159]
	ds_read_b128 v[2:5], v222 offset:16384
	ds_read_b128 v[6:9], v221 offset:16384
	s_waitcnt lgkmcnt(1)
	v_mfma_f32_32x32x16_bf16 v[144:159], v[2:5], v[172:175], v[144:159]
	s_waitcnt lgkmcnt(0)
	v_mfma_f32_32x32x16_bf16 v[144:159], v[6:9], v[176:179], v[144:159]
	ds_read_b128 v[2:5], v220 offset:16384
	ds_read_b128 v[6:9], v219 offset:16384
	s_waitcnt lgkmcnt(1)
	v_mfma_f32_32x32x16_bf16 v[144:159], v[2:5], v[180:183], v[144:159]
	s_waitcnt lgkmcnt(0)
	v_mfma_f32_32x32x16_bf16 v[144:159], v[6:9], v[188:191], v[144:159]
	s_cbranch_scc0 .LBB0_156
	v_mov_b32_e32 v0, s67
	ds_read_b32 v0, v0
	s_mov_b64 s[4:5], 0
	s_waitcnt lgkmcnt(0)
	s_nop 6
	v_fma_f32 v2, v144, s36, v0
	v_fma_f32 v3, v145, s36, v0
	v_fma_f32 v4, v146, s36, v0
	v_fma_f32 v5, v147, s36, v0
	v_fma_f32 v6, v148, s36, v0
	v_fma_f32 v7, v149, s36, v0
	v_fma_f32 v8, v150, s36, v0
	v_fma_f32 v9, v151, s36, v0
	v_fma_f32 v10, v152, s36, v0
	v_fma_f32 v11, v153, s36, v0
	v_fma_f32 v14, v154, s36, v0
	v_fma_f32 v15, v155, s36, v0
	v_fma_f32 v200, v156, s36, v0
	v_fma_f32 v201, v157, s36, v0
	v_fma_f32 v12, v158, s36, v0
	v_fma_f32 v13, v159, s36, v0

; template <bool SB>
; __device__ __forceinline__ void attn_unit(LAS unsigned char* lds, const bf16_t* qkv, bf16_t* merged, int b, int gi, int qb,
;                                           const float* gnorm, float lam, float outscale, const float* rel_bias) {
;     ...
;                     float mx = tv[0];
; #pragma unroll
;                     for (int i = 1; i < 16; ++i) mx = fmaxf(mx, tv[i]);
;                     mx = fmaxf(mx, __shfl_xor(mx, 32));
;                     if (__any(mx > m + 8.0f)) { const float mn = fmaxf(m, mx); const float corr = __builtin_amdgcn_exp2f(m - mn); m = mn; l *= corr;
; #pragma unroll
;                         for (int d = 0; d < NDV; ++d)
; #pragma unroll
;                             for (int i = 0; i < 16; ++i) O[d][i] *= corr; }
.LBB0_190:
	v_max_f32_e32 v0, v3, v3
	s_nop 7
	v_max_f32_e32 v144, v2, v2
	v_max_f32_e32 v0, v144, v0
	v_max3_f32 v0, v0, v4, v5
	v_max3_f32 v0, v0, v6, v7
	v_max3_f32 v0, v0, v8, v9
	v_max3_f32 v0, v0, v10, v11
	v_max3_f32 v0, v0, v14, v15
	v_max3_f32 v0, v0, v200, v201
	v_max3_f32 v0, v0, v12, v13
	v_mov_b32_e32 v144, v0
	v_mov_b32_e32 v145, v0
	s_nop 1
	v_permlane32_swap_b32_e32 v144, v145
	v_max_f32_e32 v0, v144, v145
	v_add_f32_e32 v144, 0x41000000, v218
	v_cmp_gt_f32_e32 vcc, v0, v144
	s_cbranch_vccz .LBB0_192
	v_max_f32_e32 v0, v0, v0
	v_max_f32_e32 v144, v218, v218
	v_max_f32_e32 v144, v144, v0
	v_sub_f32_e32 v0, v218, v144
	v_exp_f32_e32 v0, v0
	v_mov_b32_e32 v218, v144
	v_pk_mul_f32 v[142:143], v[142:143], v[0:1] op_sel_hi:[1,0]
	v_pk_mul_f32 v[140:141], v[140:141], v[0:1] op_sel_hi:[1,0]
	v_pk_mul_f32 v[138:139], v[138:139], v[0:1] op_sel_hi:[1,0]
	v_pk_mul_f32 v[136:137], v[136:137], v[0:1] op_sel_hi:[1,0]
	v_pk_mul_f32 v[134:135], v[134:135], v[0:1] op_sel_hi:[1,0]
	v_pk_mul_f32 v[132:133], v[132:133], v[0:1] op_sel_hi:[1,0]
	v_pk_mul_f32 v[130:131], v[130:131], v[0:1] op_sel_hi:[1,0]
	v_pk_mul_f32 v[128:129], v[128:129], v[0:1] op_sel_hi:[1,0]
	v_pk_mul_f32 v[126:127], v[126:127], v[0:1] op_sel_hi:[1,0]
	v_pk_mul_f32 v[124:125], v[124:125], v[0:1] op_sel_hi:[1,0]
	v_pk_mul_f32 v[122:123], v[122:123], v[0:1] op_sel_hi:[1,0]
	v_pk_mul_f32 v[120:121], v[120:121], v[0:1] op_sel_hi:[1,0]
	v_pk_mul_f32 v[118:119], v[118:119], v[0:1] op_sel_hi:[1,0]
	v_pk_mul_f32 v[116:117], v[116:117], v[0:1] op_sel_hi:[1,0]
	v_pk_mul_f32 v[114:115], v[114:115], v[0:1] op_sel_hi:[1,0]
	v_pk_mul_f32 v[112:113], v[112:113], v[0:1] op_sel_hi:[1,0]
	v_pk_mul_f32 v[110:111], v[110:111], v[0:1] op_sel_hi:[1,0]
	v_pk_mul_f32 v[108:109], v[108:109], v[0:1] op_sel_hi:[1,0]
	v_pk_mul_f32 v[106:107], v[106:107], v[0:1] op_sel_hi:[1,0]
	v_pk_mul_f32 v[104:105], v[104:105], v[0:1] op_sel_hi:[1,0]
	v_pk_mul_f32 v[102:103], v[102:103], v[0:1] op_sel_hi:[1,0]
	v_pk_mul_f32 v[100:101], v[100:101], v[0:1] op_sel_hi:[1,0]
	v_pk_mul_f32 v[98:99], v[98:99], v[0:1] op_sel_hi:[1,0]
	v_pk_mul_f32 v[96:97], v[96:97], v[0:1] op_sel_hi:[1,0]
	v_pk_mul_f32 v[94:95], v[94:95], v[0:1] op_sel_hi:[1,0]
	v_pk_mul_f32 v[92:93], v[92:93], v[0:1] op_sel_hi:[1,0]
	v_pk_mul_f32 v[90:91], v[90:91], v[0:1] op_sel_hi:[1,0]
	v_pk_mul_f32 v[88:89], v[88:89], v[0:1] op_sel_hi:[1,0]
	v_pk_mul_f32 v[86:87], v[86:87], v[0:1] op_sel_hi:[1,0]
	v_pk_mul_f32 v[84:85], v[84:85], v[0:1] op_sel_hi:[1,0]
	v_pk_mul_f32 v[82:83], v[82:83], v[0:1] op_sel_hi:[1,0]
	v_pk_mul_f32 v[80:81], v[80:81], v[0:1] op_sel_hi:[1,0]
	v_pk_mul_f32 v[78:79], v[78:79], v[0:1] op_sel_hi:[1,0]
	v_pk_mul_f32 v[76:77], v[76:77], v[0:1] op_sel_hi:[1,0]
	v_pk_mul_f32 v[74:75], v[74:75], v[0:1] op_sel_hi:[1,0]
	v_pk_mul_f32 v[72:73], v[72:73], v[0:1] op_sel_hi:[1,0]
	v_pk_mul_f32 v[70:71], v[70:71], v[0:1] op_sel_hi:[1,0]
	v_pk_mul_f32 v[68:69], v[68:69], v[0:1] op_sel_hi:[1,0]
	v_pk_mul_f32 v[66:67], v[66:67], v[0:1] op_sel_hi:[1,0]
	v_pk_mul_f32 v[64:65], v[64:65], v[0:1] op_sel_hi:[1,0]
	v_pk_mul_f32 v[62:63], v[62:63], v[0:1] op_sel_hi:[1,0]
	v_pk_mul_f32 v[60:61], v[60:61], v[0:1] op_sel_hi:[1,0]
	v_pk_mul_f32 v[58:59], v[58:59], v[0:1] op_sel_hi:[1,0]
	v_pk_mul_f32 v[56:57], v[56:57], v[0:1] op_sel_hi:[1,0]
	v_pk_mul_f32 v[54:55], v[54:55], v[0:1] op_sel_hi:[1,0]
	v_pk_mul_f32 v[52:53], v[52:53], v[0:1] op_sel_hi:[1,0]
	v_pk_mul_f32 v[50:51], v[50:51], v[0:1] op_sel_hi:[1,0]
	v_pk_mul_f32 v[48:49], v[48:49], v[0:1] op_sel_hi:[1,0]
	v_pk_mul_f32 v[46:47], v[46:47], v[0:1] op_sel_hi:[1,0]
	v_pk_mul_f32 v[44:45], v[44:45], v[0:1] op_sel_hi:[1,0]
	v_pk_mul_f32 v[42:43], v[42:43], v[0:1] op_sel_hi:[1,0]
	v_pk_mul_f32 v[40:41], v[40:41], v[0:1] op_sel_hi:[1,0]
	v_pk_mul_f32 v[38:39], v[38:39], v[0:1] op_sel_hi:[1,0]
	v_pk_mul_f32 v[36:37], v[36:37], v[0:1] op_sel_hi:[1,0]
	v_pk_mul_f32 v[34:35], v[34:35], v[0:1] op_sel_hi:[1,0]
	v_pk_mul_f32 v[32:33], v[32:33], v[0:1] op_sel_hi:[1,0]
	v_pk_mul_f32 v[30:31], v[30:31], v[0:1] op_sel_hi:[1,0]
	v_pk_mul_f32 v[28:29], v[28:29], v[0:1] op_sel_hi:[1,0]
	v_pk_mul_f32 v[26:27], v[26:27], v[0:1] op_sel_hi:[1,0]
	v_pk_mul_f32 v[24:25], v[24:25], v[0:1] op_sel_hi:[1,0]
	v_pk_mul_f32 v[22:23], v[22:23], v[0:1] op_sel_hi:[1,0]
	v_pk_mul_f32 v[20:21], v[20:21], v[0:1] op_sel_hi:[1,0]
	v_pk_mul_f32 v[18:19], v[18:19], v[0:1] op_sel_hi:[1,0]
	v_pk_mul_f32 v[16:17], v[16:17], v[0:1] op_sel_hi:[1,0]
	v_mul_f32_e32 v217, v217, v0

; #define LAS __attribute__((address_space(3)))
; #define MFMA32(a, b, c) __builtin_amdgcn_mfma_f32_32x32x16_bf16((a), (b), (c), 0, 0, 0)
; template <bool SB>
; __device__ __forceinline__ void attn_unit(LAS unsigned char* lds, const bf16_t* qkv, bf16_t* merged, int b, int gi, int qb,
;                                           const float* gnorm, float lam, float outscale, const float* rel_bias) {
;     ...
;             const int s0 = 64 * kt + 32 * kb;
;             const bool skip = SB ? (s0 >= q0 + 31 || wdone) : (s0 > q0 + 31);
;             if (!skip) {
;                 f32x16 sacc;
; #pragma unroll
;                 for (int i = 0; i < 16; ++i) sacc[i] = 0.f;
; #pragma unroll
;                 for (int s = 0; s < 8; ++s) { const bf16x8 kf = *(LAS const bf16x8*)(stage + ((kbase ^ (unsigned)(s << 5)) + kb * 16384)); sacc = MFMA32(kf, qf[s], sacc); }
;     ...
;                     float tv[16];
;                     constexpr float C = QK_SCALE * LOG2E;
;                     if (s0 + 31 + 128 <= q0) { const float cb = tab[128];
; #pragma unroll
;                         for (int i = 0; i < 16; ++i) tv[i] = sacc[i] * C + cb;
.Ldma_skip_0:
	s_add_i32 s4, s78, 0xffffff41
	s_cmp_gt_u32 s4, s52
	s_cbranch_scc1 .LBB0_148
	ds_read_b128 v[2:5], v226
	ds_read_b128 v[6:9], v225
	s_sub_i32 s4, s78, 32
	s_cmp_gt_u32 s4, s77
	s_mov_b64 s[4:5], -1
	s_waitcnt lgkmcnt(1)
	v_mfma_f32_32x32x16_bf16 v[144:159], v[2:5], v[184:187], 0
	s_waitcnt lgkmcnt(0)
	v_mfma_f32_32x32x16_bf16 v[144:159], v[6:9], v[160:163], v[144:159]
	ds_read_b128 v[2:5], v224
	ds_read_b128 v[6:9], v223
	s_waitcnt lgkmcnt(1)
	v_mfma_f32_32x32x16_bf16 v[144:159], v[2:5], v[164:167], v[144:159]
	s_waitcnt lgkmcnt(0)
	v_mfma_f32_32x32x16_bf16 v[144:159], v[6:9], v[168:171], v[144:159]
	ds_read_b128 v[2:5], v222
	ds_read_b128 v[6:9], v221
	s_waitcnt lgkmcnt(1)
	v_mfma_f32_32x32x16_bf16 v[144:159], v[2:5], v[172:175], v[144:159]
	s_waitcnt lgkmcnt(0)
	v_mfma_f32_32x32x16_bf16 v[144:159], v[6:9], v[176:179], v[144:159]
	ds_read_b128 v[2:5], v220
	ds_read_b128 v[6:9], v219
	s_waitcnt lgkmcnt(1)
	v_mfma_f32_32x32x16_bf16 v[144:159], v[2:5], v[180:183], v[144:159]
	s_waitcnt lgkmcnt(0)
	v_mfma_f32_32x32x16_bf16 v[144:159], v[6:9], v[188:191], v[144:159]
	s_cbranch_scc1 .LBB0_196
	v_mov_b32_e32 v0, s67
	ds_read_b32 v0, v0
	s_mov_b64 s[4:5], 0
	s_waitcnt lgkmcnt(0)
	s_nop 6
	v_fma_f32 v2, v144, s36, v0
	v_fma_f32 v3, v145, s36, v0
	v_fma_f32 v4, v146, s36, v0
	v_fma_f32 v5, v147, s36, v0
	v_fma_f32 v6, v148, s36, v0
	v_fma_f32 v7, v149, s36, v0
	v_fma_f32 v8, v150, s36, v0
	v_fma_f32 v9, v151, s36, v0
	v_fma_f32 v10, v152, s36, v0
	v_fma_f32 v11, v153, s36, v0
	v_fma_f32 v12, v154, s36, v0
	v_fma_f32 v13, v155, s36, v0
	v_fma_f32 v200, v156, s36, v0
	v_fma_f32 v201, v157, s36, v0
	v_fma_f32 v14, v158, s36, v0
	v_fma_f32 v15, v159, s36, v0

; template <bool SB>
; __device__ __forceinline__ void attn_unit(LAS unsigned char* lds, const bf16_t* qkv, bf16_t* merged, int b, int gi, int qb,
;                                           const float* gnorm, float lam, float outscale, const float* rel_bias) {
;     ...
;                     float mx = tv[0];
; #pragma unroll
;                     for (int i = 1; i < 16; ++i) mx = fmaxf(mx, tv[i]);
;                     mx = fmaxf(mx, __shfl_xor(mx, 32));
;                     if (__any(mx > m + 8.0f)) { const float mn = fmaxf(m, mx); const float corr = __builtin_amdgcn_exp2f(m - mn); m = mn; l *= corr;
; #pragma unroll
;                         for (int d = 0; d < NDV; ++d)
; #pragma unroll
;                             for (int i = 0; i < 16; ++i) O[d][i] *= corr; }
.LBB0_230:
	v_max_f32_e32 v0, v3, v3
	s_nop 7
	v_max_f32_e32 v144, v2, v2
	v_max_f32_e32 v0, v144, v0
	v_max3_f32 v0, v0, v4, v5
	v_max3_f32 v0, v0, v6, v7
	v_max3_f32 v0, v0, v8, v9
	v_max3_f32 v0, v0, v10, v11
	v_max3_f32 v0, v0, v12, v13
	v_max3_f32 v0, v0, v200, v201
	v_max3_f32 v0, v0, v14, v15
	v_mov_b32_e32 v144, v0
	v_mov_b32_e32 v145, v0
	s_nop 1
	v_permlane32_swap_b32_e32 v144, v145
	v_max_f32_e32 v0, v144, v145
	v_add_f32_e32 v144, 0x41000000, v218
	v_cmp_gt_f32_e32 vcc, v0, v144
	s_cbranch_vccz .LBB0_147
	v_max_f32_e32 v0, v0, v0
	v_max_f32_e32 v144, v218, v218
	v_max_f32_e32 v144, v144, v0
	v_sub_f32_e32 v0, v218, v144
	v_exp_f32_e32 v0, v0
	v_mov_b32_e32 v218, v144
	v_pk_mul_f32 v[142:143], v[142:143], v[0:1] op_sel_hi:[1,0]
	v_pk_mul_f32 v[140:141], v[140:141], v[0:1] op_sel_hi:[1,0]
	v_pk_mul_f32 v[138:139], v[138:139], v[0:1] op_sel_hi:[1,0]
	v_pk_mul_f32 v[136:137], v[136:137], v[0:1] op_sel_hi:[1,0]
	v_pk_mul_f32 v[134:135], v[134:135], v[0:1] op_sel_hi:[1,0]
	v_pk_mul_f32 v[132:133], v[132:133], v[0:1] op_sel_hi:[1,0]
	v_pk_mul_f32 v[130:131], v[130:131], v[0:1] op_sel_hi:[1,0]
	v_pk_mul_f32 v[128:129], v[128:129], v[0:1] op_sel_hi:[1,0]
	v_pk_mul_f32 v[126:127], v[126:127], v[0:1] op_sel_hi:[1,0]
	v_pk_mul_f32 v[124:125], v[124:125], v[0:1] op_sel_hi:[1,0]
	v_pk_mul_f32 v[122:123], v[122:123], v[0:1] op_sel_hi:[1,0]
	v_pk_mul_f32 v[120:121], v[120:121], v[0:1] op_sel_hi:[1,0]
	v_pk_mul_f32 v[118:119], v[118:119], v[0:1] op_sel_hi:[1,0]
	v_pk_mul_f32 v[116:117], v[116:117], v[0:1] op_sel_hi:[1,0]
	v_pk_mul_f32 v[114:115], v[114:115], v[0:1] op_sel_hi:[1,0]
	v_pk_mul_f32 v[112:113], v[112:113], v[0:1] op_sel_hi:[1,0]
	v_pk_mul_f32 v[110:111], v[110:111], v[0:1] op_sel_hi:[1,0]
	v_pk_mul_f32 v[108:109], v[108:109], v[0:1] op_sel_hi:[1,0]
	v_pk_mul_f32 v[106:107], v[106:107], v[0:1] op_sel_hi:[1,0]
	v_pk_mul_f32 v[104:105], v[104:105], v[0:1] op_sel_hi:[1,0]
	v_pk_mul_f32 v[102:103], v[102:103], v[0:1] op_sel_hi:[1,0]
	v_pk_mul_f32 v[100:101], v[100:101], v[0:1] op_sel_hi:[1,0]
	v_pk_mul_f32 v[98:99], v[98:99], v[0:1] op_sel_hi:[1,0]
	v_pk_mul_f32 v[96:97], v[96:97], v[0:1] op_sel_hi:[1,0]
	v_pk_mul_f32 v[94:95], v[94:95], v[0:1] op_sel_hi:[1,0]
	v_pk_mul_f32 v[92:93], v[92:93], v[0:1] op_sel_hi:[1,0]
	v_pk_mul_f32 v[90:91], v[90:91], v[0:1] op_sel_hi:[1,0]
	v_pk_mul_f32 v[88:89], v[88:89], v[0:1] op_sel_hi:[1,0]
	v_pk_mul_f32 v[86:87], v[86:87], v[0:1] op_sel_hi:[1,0]
	v_pk_mul_f32 v[84:85], v[84:85], v[0:1] op_sel_hi:[1,0]
	v_pk_mul_f32 v[82:83], v[82:83], v[0:1] op_sel_hi:[1,0]
	v_pk_mul_f32 v[80:81], v[80:81], v[0:1] op_sel_hi:[1,0]
	v_pk_mul_f32 v[78:79], v[78:79], v[0:1] op_sel_hi:[1,0]
	v_pk_mul_f32 v[76:77], v[76:77], v[0:1] op_sel_hi:[1,0]
	v_pk_mul_f32 v[74:75], v[74:75], v[0:1] op_sel_hi:[1,0]
	v_pk_mul_f32 v[72:73], v[72:73], v[0:1] op_sel_hi:[1,0]
	v_pk_mul_f32 v[70:71], v[70:71], v[0:1] op_sel_hi:[1,0]
	v_pk_mul_f32 v[68:69], v[68:69], v[0:1] op_sel_hi:[1,0]
	v_pk_mul_f32 v[66:67], v[66:67], v[0:1] op_sel_hi:[1,0]
	v_pk_mul_f32 v[64:65], v[64:65], v[0:1] op_sel_hi:[1,0]
	v_pk_mul_f32 v[62:63], v[62:63], v[0:1] op_sel_hi:[1,0]
	v_pk_mul_f32 v[60:61], v[60:61], v[0:1] op_sel_hi:[1,0]
	v_pk_mul_f32 v[58:59], v[58:59], v[0:1] op_sel_hi:[1,0]
	v_pk_mul_f32 v[56:57], v[56:57], v[0:1] op_sel_hi:[1,0]
	v_pk_mul_f32 v[54:55], v[54:55], v[0:1] op_sel_hi:[1,0]
	v_pk_mul_f32 v[52:53], v[52:53], v[0:1] op_sel_hi:[1,0]
	v_pk_mul_f32 v[50:51], v[50:51], v[0:1] op_sel_hi:[1,0]
	v_pk_mul_f32 v[48:49], v[48:49], v[0:1] op_sel_hi:[1,0]
	v_pk_mul_f32 v[46:47], v[46:47], v[0:1] op_sel_hi:[1,0]
	v_pk_mul_f32 v[44:45], v[44:45], v[0:1] op_sel_hi:[1,0]
	v_pk_mul_f32 v[42:43], v[42:43], v[0:1] op_sel_hi:[1,0]
	v_pk_mul_f32 v[40:41], v[40:41], v[0:1] op_sel_hi:[1,0]
	v_pk_mul_f32 v[38:39], v[38:39], v[0:1] op_sel_hi:[1,0]
	v_pk_mul_f32 v[36:37], v[36:37], v[0:1] op_sel_hi:[1,0]
	v_pk_mul_f32 v[34:35], v[34:35], v[0:1] op_sel_hi:[1,0]
	v_pk_mul_f32 v[32:33], v[32:33], v[0:1] op_sel_hi:[1,0]
	v_pk_mul_f32 v[30:31], v[30:31], v[0:1] op_sel_hi:[1,0]
	v_pk_mul_f32 v[28:29], v[28:29], v[0:1] op_sel_hi:[1,0]
	v_pk_mul_f32 v[26:27], v[26:27], v[0:1] op_sel_hi:[1,0]
	v_pk_mul_f32 v[24:25], v[24:25], v[0:1] op_sel_hi:[1,0]
	v_pk_mul_f32 v[22:23], v[22:23], v[0:1] op_sel_hi:[1,0]
	v_pk_mul_f32 v[20:21], v[20:21], v[0:1] op_sel_hi:[1,0]
	v_pk_mul_f32 v[18:19], v[18:19], v[0:1] op_sel_hi:[1,0]
	v_pk_mul_f32 v[16:17], v[16:17], v[0:1] op_sel_hi:[1,0]
	v_mul_f32_e32 v217, v217, v0
	s_branch .LBB0_147
